# v31 + P0 x-pass: loop-head vmcnt(1)/vmcnt(0) (needed only on first entry) hoisted to the preheader so steady-state iterations issue the next prefetch without waiting for the previous store acks
# speedup vs baseline: 1.0124x; 1.0124x over previous
; __device__ __forceinline__ float wave_sum(float v) {
; #pragma unroll
;     for (int o = 1; o < 64; o <<= 1) v += __shfl_xor(v, o);
;     return v;
; __global__ void __launch_bounds__(512, 2) fwd_kernel(Args args) {
;     ...
;             auto xrowp = [&](int m) -> const f32x4* { return (const f32x4*)((m < NB_PROMPT * SEQ) ? x_p + (size_t)m * DM : x_s + (size_t)(m - NB_PROMPT * SEQ) * DM) + lane; };
;             f32x4 v[4], w[4], nv[4], nw[4];
;             { const f32x4* a = xrowp(gw); const f32x4* b = xrowp(gw + NGW);
; #pragma unroll
;               for (int j = 0; j < 4; ++j) { nv[j] = __builtin_nontemporal_load(a + 64 * j); nw[j] = __builtin_nontemporal_load(b + 64 * j); } }
;             for (int m = gw; m < M; m += 2 * NGW) {
;                 const int m2 = m + NGW, mn = m + 2 * NGW;
; #pragma unroll
;                 for (int j = 0; j < 4; ++j) { v[j] = nv[j]; w[j] = nw[j]; }
;                 if (mn < M) { const f32x4* a = xrowp(mn); const f32x4* b = xrowp(mn + NGW);
; #pragma unroll
;                     for (int j = 0; j < 4; ++j) { nv[j] = __builtin_nontemporal_load(a + 64 * j); nw[j] = __builtin_nontemporal_load(b + 64 * j); } }
.LBB0_9:
	s_or_b64 exec, exec, s[2:3]
	s_lshl_b32 s0, s86, 2
	s_bfe_u32 s60, s6, 0x20006
	s_or_b32 s7, s0, s60
	s_lshl_b32 s33, s15, 2
	s_cmpk_lt_u32 s6, 0x100
	s_mov_b64 s[0:1], -1
	s_waitcnt lgkmcnt(0)
	s_barrier
	s_cbranch_scc0 .LBB0_21
	s_cmp_gt_i32 s7, 0xbfff
	s_cbranch_scc1 .LBB0_20
	s_add_i32 s0, s7, 0xffff8000
	s_ashr_i32 s1, s7, 31
	s_cmp_lt_i32 s7, 0x8000
	s_cselect_b32 s1, s1, 0
	s_cselect_b32 s0, s7, s0
	s_cselect_b32 s2, s37, s39
	s_cselect_b32 s3, s36, s38
	s_lshl_b64 s[0:1], s[0:1], 12
	s_add_u32 s0, s3, s0
	s_addc_u32 s1, s2, s1
	s_add_i32 s2, s7, s33
	s_add_i32 s4, s2, 0xffff8000
	s_ashr_i32 s3, s2, 31
	s_cmp_lt_i32 s2, 0x8000
	s_cselect_b32 s3, s3, 0
	s_cselect_b32 s2, s2, s4
	s_cselect_b32 s4, s37, s39
	s_cselect_b32 s5, s36, s38
	s_lshl_b64 s[2:3], s[2:3], 12
	v_lshlrev_b32_e32 v1, 4, v162
	s_add_u32 s2, s5, s2
	s_addc_u32 s3, s4, s3
	global_load_dwordx4 v[30:33], v1, s[0:1] nt
	global_load_dwordx4 v[22:25], v1, s[0:1] offset:1024 nt
	global_load_dwordx4 v[14:17], v1, s[2:3] offset:1024 nt
	global_load_dwordx4 v[26:29], v1, s[2:3] nt
	global_load_dwordx4 v[2:5], v1, s[2:3] offset:3072 nt
	global_load_dwordx4 v[6:9], v1, s[2:3] offset:2048 nt
	global_load_dwordx4 v[18:21], v1, s[0:1] offset:2048 nt
	global_load_dwordx4 v[10:13], v1, s[0:1] offset:3072 nt
	v_mbcnt_lo_u32_b32 v34, -1, 0
	v_mbcnt_hi_u32_b32 v34, -1, v34
	v_and_b32_e32 v35, 64, v34
	v_xor_b32_e32 v36, 1, v34
	v_add_u32_e32 v35, 64, v35
	v_xor_b32_e32 v37, 2, v34
	v_cmp_lt_i32_e32 vcc, v36, v35
	v_xor_b32_e32 v38, 4, v34
	v_xor_b32_e32 v39, 8, v34
	v_cndmask_b32_e32 v36, v34, v36, vcc
	v_cmp_lt_i32_e32 vcc, v37, v35
	v_xor_b32_e32 v40, 16, v34
	v_xor_b32_e32 v41, 32, v34
	v_cndmask_b32_e32 v37, v34, v37, vcc
	v_cmp_lt_i32_e32 vcc, v38, v35
	v_mov_b32_e32 v67, 0
	v_lshlrev_b32_e32 v66, 3, v162
	v_cndmask_b32_e32 v38, v34, v38, vcc
	v_cmp_lt_i32_e32 vcc, v39, v35
	v_lshl_add_u64 v[68:69], s[34:35], 0, v[66:67]
	v_lshlrev_b32_e32 v66, 2, v36
	v_cndmask_b32_e32 v39, v34, v39, vcc
	v_cmp_lt_i32_e32 vcc, v40, v35
	v_lshlrev_b32_e32 v76, 2, v37
	v_lshlrev_b32_e32 v77, 2, v38
	v_cndmask_b32_e32 v40, v34, v40, vcc
	v_cmp_lt_i32_e32 vcc, v41, v35
	v_lshlrev_b32_e32 v78, 2, v39
	v_lshlrev_b32_e32 v79, 2, v40
	v_cndmask_b32_e32 v34, v34, v41, vcc
	v_lshlrev_b32_e32 v80, 2, v34
	v_cmp_ne_u32_e64 s[2:3], 0, v162
	s_mul_i32 s6, s15, 12
	v_lshlrev_b32_e32 v1, 4, v162
	v_mov_b32_e32 v74, 0x358637bd
	s_mov_b32 s61, 0xf800000
	v_mov_b32_e32 v75, 0x260
	s_mov_b32 s76, s7
	s_lshl_b32 s64, s15, 3
	s_waitcnt vmcnt(5)
	v_mov_b64_e32 v[40:41], v[16:17]
	s_waitcnt vmcnt(4)
	v_mov_b64_e32 v[36:37], v[28:29]
	s_waitcnt vmcnt(3)
	v_mov_b64_e32 v[48:49], v[4:5]
	s_waitcnt vmcnt(2)
	v_mov_b64_e32 v[44:45], v[8:9]
	v_mov_b64_e32 v[34:35], v[26:27]
	v_mov_b64_e32 v[38:39], v[14:15]
	v_mov_b64_e32 v[42:43], v[6:7]
	v_mov_b64_e32 v[46:47], v[2:3]
	s_waitcnt vmcnt(0)
	s_branch .LBB0_13

; __global__ void __launch_bounds__(512, 2) fwd_kernel(Args args) {
;     ...
;             for (int m = gw; m < M; m += 2 * NGW) {
;                 const int m2 = m + NGW, mn = m + 2 * NGW;
; #pragma unroll
;                 for (int j = 0; j < 4; ++j) { v[j] = nv[j]; w[j] = nw[j]; }
;                 if (mn < M) { const f32x4* a = xrowp(mn); const f32x4* b = xrowp(mn + NGW);
; #pragma unroll
;                     for (int j = 0; j < 4; ++j) { nv[j] = __builtin_nontemporal_load(a + 64 * j); nw[j] = __builtin_nontemporal_load(b + 64 * j); } }
.LBB0_13:
	s_add_i32 s0, s64, s76
	s_cmp_gt_i32 s0, 0xbfff
	v_mov_b32_e32 v50, v30
	v_mov_b32_e32 v51, v31
	v_mov_b32_e32 v52, v32
	v_mov_b32_e32 v53, v33
	v_mov_b32_e32 v54, v22
	v_mov_b32_e32 v55, v23
	v_mov_b32_e32 v56, v24
	v_mov_b32_e32 v57, v25
	v_mov_b32_e32 v58, v18
	v_mov_b32_e32 v59, v19
	v_mov_b32_e32 v60, v20
	v_mov_b32_e32 v61, v21
	v_mov_b32_e32 v62, v10
	v_mov_b32_e32 v63, v11
	v_mov_b32_e32 v64, v12
	v_mov_b32_e32 v65, v13
	s_cbranch_scc1 .LBB0_15
	s_add_i32 s4, s0, 0xffff8000
	s_ashr_i32 s1, s0, 31
	s_cmp_lt_i32 s0, 0x8000
	s_cselect_b32 s1, s1, 0
	s_cselect_b32 s0, s0, s4
	s_cselect_b32 s4, s37, s39
	s_cselect_b32 s5, s36, s38
	s_lshl_b64 s[0:1], s[0:1], 12
	s_add_u32 s0, s5, s0
	s_addc_u32 s1, s4, s1
	s_add_i32 s4, s6, s76
	s_add_i32 s8, s4, 0xffff8000
	s_ashr_i32 s5, s4, 31
	s_cmp_lt_i32 s4, 0x8000
	s_cselect_b32 s5, s5, 0
	s_cselect_b32 s4, s4, s8
	s_cselect_b32 s8, s37, s39
	s_cselect_b32 s9, s36, s38
	s_lshl_b64 s[4:5], s[4:5], 12
	s_add_u32 s4, s9, s4
	s_addc_u32 s5, s8, s5
	global_load_dwordx4 v[50:53], v1, s[0:1] nt
	global_load_dwordx4 v[54:57], v1, s[0:1] offset:1024 nt
	global_load_dwordx4 v[34:37], v1, s[4:5] nt
	global_load_dwordx4 v[38:41], v1, s[4:5] offset:1024 nt
	global_load_dwordx4 v[58:61], v1, s[0:1] offset:2048 nt
	global_load_dwordx4 v[62:65], v1, s[0:1] offset:3072 nt
	global_load_dwordx4 v[42:45], v1, s[4:5] offset:2048 nt
	global_load_dwordx4 v[46:49], v1, s[4:5] offset:3072 nt
